# grid barrier: leader no longer re-publishes the per-XCD generation (nobody waits on it any more), so its exit wait covers only the cache invalidate
# baseline (speedup 1.0000x reference)
; __device__ __forceinline__ unsigned xb_ld(unsigned* p)              { return __hip_atomic_load(p, __ATOMIC_RELAXED, __HIP_MEMORY_SCOPE_AGENT); }
; __device__ __forceinline__ unsigned xb_add(unsigned* p, unsigned v) { return __hip_atomic_fetch_add(p, v, __ATOMIC_RELAXED, __HIP_MEMORY_SCOPE_AGENT); }
; #define XB_SPIN(cond, bar) do { unsigned _sp = 0; while (cond) { __builtin_amdgcn_s_sleep(0); \
;     if ((++_sp & 255u) == 0u) { if (xb_ld(&(bar)[XB_TMO])) break; if (_sp > XB_SPIN_CAP) { atomicAdd(&(bar)[XB_TMO], 1u); break; } } } } while (0)
; __device__ __forceinline__ void xcd_barrier(const XcdBarrier& b) {
;     ...
;             const unsigned og = xb_add(&bar[XB_TOP], 1u);
;             const unsigned tg = og / nx;
;             if (og + 1u == (tg + 1u) * nx) xb_add(&bar[XB_TOPGEN], 1u);
;             else XB_SPIN(xb_ld(&bar[XB_TOPGEN]) == tg, bar);
;             __builtin_amdgcn_fence(__ATOMIC_ACQUIRE, "agent");
;             xb_add(&bar[XB_XGEN(b.x)], 1u);
;             asm volatile("s_waitcnt vmcnt(0)" ::: "memory");
.LBB0_186:
	s_or_b64 exec, exec, s[0:1]
	s_mov_b64 s[0:1], exec
	v_mbcnt_lo_u32_b32 v0, s0, 0
	v_mbcnt_hi_u32_b32 v0, s1, v0
	v_cmp_eq_u32_e32 vcc, 0, v0
	s_waitcnt vmcnt(0)
	buffer_inv sc1
	s_and_saveexec_b64 s[2:3], vcc
	s_cbranch_execz .LBB0_188
	s_bcnt1_i32_b64 s0, s[0:1]
	v_mov_b32_e32 v0, s0
	v_readlane_b32 s0, v252, 5
	v_readlane_b32 s1, v252, 6
	s_nop 4
	s_nop 0
